# v085 + layer-0 out-proj->ffn-down stream relocated into the idle output buffer (out + 16 MiB x + 8 MiB): k7->k0' boundary XCD-local too; 9 XCD-local barriers (t=0,4,5,6,7,8,12,13,14)
# speedup vs baseline: 1.0193x; 1.0023x over previous
;     __device__ __forceinline__ const float* in(int i) const { return *(const __attribute__((address_space(4))) cfptr_t*)(p + 8 * i); }
;     __device__ __forceinline__ float* out() const { return *(const __attribute__((address_space(4))) fptr_t*)(p + 256); }
;     __device__ __forceinline__ unsigned char* ws() const { return *(const __attribute__((address_space(4))) ucptr_t*)(p + 264); }
; __device__ __forceinline__ void run_phase(const KA& A, const Ctx& F, int ph) {
;     ...
;         if (k == 0) { g = pg8::Gemm{XN, (const bf16*)(wl + WO_IN), NIN, D, D, D}; E.kind = 0; }
;         else if (k == 3) { g = pg8::Gemm{PS + C_SSM, (const bf16*)(wl + WO_GLU), 512, 256, PSW, 256}; E.kind = 4; }
;         else if (k == 5) { g = pg8::Gemm{XN, (const bf16*)(wl + WO_OUT), D, D, D, D}; E.kind = 2; E.gi = (2 * l) << 2; E.out = hmid; }
;         else if (k == 6) { g = pg8::Gemm{(const bf16*)(F.ws + WS_GT), (const bf16*)(wl + WO_GU), 2 * FFH, D, D, D}; E.kind = 3; }
;         else { g = pg8::Gemm{PS, (const bf16*)(wl + WO_DN), D, FFH, FFH, FFH}; E.kind = 2; E.base = hmid;
;                E.gi = ((2 * l + 1) << 2) | 1 | ((l == DEPTH - 1) ? 2 : 0); E.gain = (l == DEPTH - 1) ? A.in(31) : A.in(1) + (l + 1) * D; }
.LBB0_224:
	s_and_b64 vcc, exec, s[16:17]
	s_cbranch_vccz .LBB0_232
	s_add_u32 s4, s84, 0xe00000
	v_readlane_b32 s6, v254, 2
	s_addc_u32 s5, s85, 0
	s_mov_b64 s[0:1], -1
	s_mov_b32 s64, 2
	s_mov_b32 s19, 4
	s_mov_b64 s[8:9], s[28:29]
	s_mov_b32 s18, s11
	v_readlane_b32 s7, v254, 3
	s_cmp_lt_u32 s70, 9
	s_cbranch_scc0 .Lhm_l1
	v_readlane_b32 s6, v253, 60
	v_readlane_b32 s7, v253, 61
	s_and_b32 s16, s80, 7
	s_lshl_b32 s16, s16, 23
	s_add_u32 s6, s6, s16
	s_addc_u32 s7, s7, 0
	s_add_u32 s6, s6, 0x800000
	s_addc_u32 s7, s7, 0
.Lhm_l1:
	s_mov_b64 s[16:17], 0
.LBB0_226:
	s_and_b64 vcc, exec, s[16:17]
	s_cbranch_vccz .LBB0_233
	s_cmp_gt_i32 s25, 2
	s_mov_b64 s[12:13], -1
	s_cbranch_scc0 .LBB0_230
	s_cmp_eq_u32 s25, 3
	s_mov_b64 s[14:15], -1
	s_cbranch_scc0 .LBB0_234
	s_add_u32 s4, s84, 0x2080000
	v_readlane_b32 s12, v253, 60
	s_addc_u32 s5, s85, 0
	v_readlane_b32 s14, v253, 62
	v_readlane_b32 s13, v253, 61
	v_readlane_b32 s15, v253, 63
	s_add_u32 s8, s14, 0x8401400
	s_addc_u32 s9, s15, 0
	s_mov_b64 s[14:15], 0
	s_mov_b64 s[6:7], s[12:13]
	s_mov_b64 s[12:13], 0

;     __device__ __forceinline__ const float* in(int i) const { return *(const __attribute__((address_space(4))) cfptr_t*)(p + 8 * i); }
; __device__ __forceinline__ void run_phase(const KA& A, const Ctx& F, int ph) {
;     ...
;         else { g = pg8::Gemm{PS, (const bf16*)(wl + WO_DN), D, FFH, FFH, FFH}; E.kind = 2; E.base = hmid;
;                E.gi = ((2 * l + 1) << 2) | 1 | ((l == DEPTH - 1) ? 2 : 0); E.gain = (l == DEPTH - 1) ? A.in(31) : A.in(1) + (l + 1) * D; }
.LBB0_240:
	s_or_b32 s18, s6, s11
	v_readlane_b32 s8, v253, 60
	v_readlane_b32 s9, v253, 61
	s_mov_b64 s[6:7], s[8:9]
	v_readlane_b32 s8, v254, 2
	v_readlane_b32 s9, v254, 3
	s_cmp_lt_u32 s70, 9
	s_cbranch_scc0 .Lstr_fin
	s_and_b32 s0, s80, 7
	s_lshl_b32 s0, s0, 23
	s_add_u32 s6, s6, s0
	s_addc_u32 s7, s7, 0
	s_add_u32 s8, s6, 0x800000
	s_addc_u32 s9, s7, 0
.Lstr_fin:
	s_movk_i32 s20, 0xb00
	v_writelane_b32 v254, s8, 0
	s_mov_b32 s19, 4
	s_mov_b32 s65, 0
	s_mov_b64 s[12:13], 0
	s_mov_b32 s64, 2
	s_mov_b64 s[0:1], -1
	v_writelane_b32 v254, s9, 1
	s_mov_b64 s[8:9], s[82:83]
	s_movk_i32 s16, 0xb00
	v_readlane_b32 s10, v253, 62
	v_readlane_b32 s11, v253, 63

; __global__ void __launch_bounds__(NTHREADS, 2) mega_fwd(Args args) {
;     ...
;         if (ph + 1 < args.ph_hi) {
;     ...
;             for (int e_ = 0; e_ < EXTRA_SYNCS; ++e_) { XcdBarrier b2 = bar; asm volatile("" : "+s"(b2.bar)); int tb_; asm volatile("v_mbcnt_lo_u32_b32 %0, -1, 0\n\tv_mbcnt_hi_u32_b32 %0, -1, %0\n\tv_or_b32 %0, %1, %0" : "=&v"(tb_) : "s"(wv0 << 6)); xcd_barrier(b2, tb_); }
;     ...
;             if (args.ph_lo < 0) { __threadfence(); cg::this_grid().sync(); }
;             { XcdBarrier b2 = bar; asm volatile("" : "+s"(b2.bar)); int tb_; asm volatile("v_mbcnt_lo_u32_b32 %0, -1, 0\n\tv_mbcnt_hi_u32_b32 %0, -1, %0\n\tv_or_b32 %0, %1, %0" : "=&v"(tb_) : "s"(wv0 << 6)); xcd_barrier(b2, tb_); } }
.LBB0_552:
	s_andn2_saveexec_b64 s[4:5], s[4:5]
	s_cbranch_execz .LBB0_8
	s_add_i32 s4, s70, -2
	s_cmp_lt_u32 s4, 15
	s_cbranch_scc0 .Lxb_global
	s_lshr_b32 s5, 0x71f1, s4
	s_and_b32 s5, s5, 1
	s_cbranch_scc0 .Lxb_global
	v_readfirstlane_b32 s5, v18
	s_cmp_eq_u32 s5, 0
	s_cbranch_scc0 .Lxb_global
	s_mov_b64 s[0:1], exec
	s_branch .LBB0_7
